# attention loops: the static priority raise moved from the younger wave half (waves 4-7) to the older half (waves 0-3) - per-half A/B of the one-static-raise lever
# baseline (speedup 1.0000x reference)
; #define LAS __attribute__((address_space(3)))
; #define GAS __attribute__((address_space(1)))
; #define A2_ISSUE_K(t) do { int tc_ = (t); tc_ = tc_ < t1 ? tc_ : t1 - 1; const GAS bf16_t* kp_ = Kg + (row0 + 64 * (size_t)tc_) * kld; \
;         _Pragma("unroll") for (int i = 0; i < NKL; ++i) kst[i] = *(const GAS u32x4*)(kp_ + ksrc[i]); } while (0)
; #define A2_ISSUE_V(t) do { int tc_ = (t); tc_ = tc_ < t1 ? tc_ : t1 - 1; const GAS bf16_t* vp_ = Vg + (row0 + 64 * (size_t)tc_) * vld; \
;         _Pragma("unroll") for (int i = 0; i < NVL; ++i) vst[i] = *(const GAS u32x4*)(vp_ + vsrc[i]); } while (0)
; #define A2_COMMIT_K(slot) do { LAS unsigned char* bb_ = lds + (slot) * KSTG; _Pragma("unroll") for (int i = 0; i < NKL; ++i) *(LAS u32x4*)(bb_ + kdst[i]) = kst[i]; } while (0)
; template <int MODE> __device__ __forceinline__ void attn_unit4(LAS unsigned char* lds, const int uidx, const AttnArgs& A) {
;     ...
;     if (MODE != 1) {
;         const int rel = tid - 256; const int bk = t5_bucket_dev(rel);
;         if (MODE == 0) { tab[tid] = A.rel_bias[bk * 8 + hx] * LOG2E; }
;         else { const bool okw = (rel <= 128 && rel >= -128);
;             tab[tid] = okw ? A.rel_bias[bk * 8 + 4 + 2 * hx] * LOG2E : negbig; tab[512 + tid] = okw ? A.rel_bias[bk * 8 + 4 + 2 * hx + 1] * LOG2E : negbig; }
;     }
;     const int qslot0 = qb * 128 + qg * 32;
;     bf16x8 qf[NKC];
;     { const GAS bf16_t* qp = Qg + (row0 + qslot0 + r32) * DIN + hi * 8;
; #pragma unroll
;       for (int kc = 0; kc < NKC; ++kc) qf[kc] = *(const GAS bf16x8*)(qp + kc * 16); }
;     ...
;     {
;       u32x4 kst2[NKL];
;       A2_ISSUE_K(t0); A2_ISSUE_V(t0);
;       { const GAS bf16_t* kp_ = Kg + (row0 + 64 * (size_t)(t0 + 1)) * kld;
; #pragma unroll
;         for (int i = 0; i < NKL; ++i) kst2[i] = *(const GAS u32x4*)(kp_ + ksrc[i]); }
;       A2_COMMIT_K(t0 & 1); A2_COMMIT_V(0);
;       { LAS unsigned char* bb_ = lds + ((t0 + 1) & 1) * KSTG;
; #pragma unroll
;         for (int i = 0; i < NKL; ++i) *(LAS u32x4*)(bb_ + kdst[i]) = kst2[i]; } }
;     __syncthreads();
;     float tabL = 0.f, tabR = 0.f; if (MODE == 0) { tabL = mytab[0]; tabR = mytab[511]; }
;     f32x16 s0, s1, n0, n1; u32x4 pk[4]; float fprev = 1.0f, fcur = 1.0f;
;     ...
;     float cbc; bool nearc;
;     A2_TILE_BIAS(t0, cbc, nearc);
;     { const float zero_ = 0.f; A2_QK(s0, s1, t0 & 1, zero_); }
;     __syncthreads();
.LBB0_930:
	s_or_b64 exec, exec, s[0:1]
	s_mul_i32 s0, s38, 0x41
	s_sub_i32 s0, s5, s0
	s_ashr_i32 s14, s15, 6
	s_ashr_i32 s40, s15, 8
	s_and_b32 s15, s0, 0xffff
	s_lshr_b32 s0, s7, 19
	s_mul_i32 s5, s0, 0x2080
	s_lshl_b32 s0, s6, 7
	s_add_u32 s6, s16, s0
	s_addc_u32 s7, s17, 0
	s_add_i32 s4, s40, s4
	s_lshl_b32 s0, s4, 6
	s_ashr_i32 s1, s0, 31
	s_lshl_b64 s[8:9], s[0:1], 1
	s_add_u32 s8, s16, s8
	s_addc_u32 s9, s17, s9
	s_lshl_b32 s41, s15, 1
	s_add_i32 s62, s41, -2
	s_cmp_lt_u32 s15, 2
	s_cselect_b64 vcc, -1, 0
	s_and_b64 s[26:27], vcc, exec
	s_cselect_b32 s30, 1, s62
	s_lshl_b32 s26, s14, 5
	s_lshl_b32 s15, s15, 7
	s_and_b32 s26, s26, 0x60
	s_min_u32 s69, s41, 0x7e
	s_add_i32 s41, 0, 0x1b800
	s_or_b32 s15, s26, s15
	v_and_b32_e32 v34, 31, v2
	v_lshl_add_u32 v0, v2, 2, s41
	s_add_i32 s26, s15, s5
	v_bfe_u32 v6, v2, 5, 1
	ds_write_b32 v0, v3 offset:2048
	v_or_b32_e32 v130, s26, v34
	v_mov_b64_e32 v[4:5], s[8:9]
	v_ashrrev_i32_e32 v3, 31, v2
	v_mad_u64_u32 v[4:5], s[8:9], v130, s45, v[4:5]
	v_lshlrev_b32_e32 v0, 4, v6
	v_lshrrev_b32_e32 v3, 29, v3
	v_lshl_add_u64 v[4:5], v[4:5], 0, v[0:1]
	v_add_u32_e32 v3, v2, v3
	global_load_dwordx4 v[82:85], v[4:5], off offset:3072
	global_load_dwordx4 v[86:89], v[4:5], off offset:3104
	global_load_dwordx4 v[90:93], v[4:5], off offset:3136
	global_load_dwordx4 v[94:97], v[4:5], off offset:3168
	v_ashrrev_i32_e32 v5, 3, v3
	v_and_b32_e32 v3, -8, v3
	s_movk_i32 s8, 0x9a0
	v_sub_u32_e32 v3, v2, v3
	v_mul_lo_u32 v4, v5, s8
	s_movk_i32 s8, 0x140
	s_add_i32 s65, s69, 4
	v_lshlrev_b32_e32 v14, 4, v3
	v_mul_lo_u32 v15, v5, s8
	s_movk_i32 s73, 0x90
	s_lshl_b32 s63, s40, 11
	s_add_i32 s69, s69, 3
	v_mad_u64_u32 v[132:133], s[8:9], v5, s73, v[14:15]
	s_cmp_lt_i32 s30, s65
	s_cselect_b32 s8, s30, s69
	s_ashr_i32 s9, s8, 31
	s_lshl_b64 s[8:9], s[8:9], 6
	s_add_u32 s8, s8, s5
	s_addc_u32 s9, s9, 0
	s_mulk_i32 s9, 0x1340
	s_mul_hi_u32 s26, s8, 0x1340
	s_add_i32 s26, s26, s9
	s_mulk_i32 s8, 0x1340
	v_lshl_add_u32 v4, v3, 3, v4
	s_add_u32 s8, s6, s8
	s_addc_u32 s9, s7, s26
	v_ashrrev_i32_e32 v5, 31, v4
	s_add_i32 s26, s30, 1
	v_lshlrev_b64 v[134:135], 1, v[4:5]
	s_ashr_i32 s27, s26, 31
	v_lshlrev_b32_e32 v133, 2, v6
	v_lshl_add_u64 v[6:7], s[8:9], 0, v[134:135]
	s_lshl_b64 s[8:9], s[26:27], 6
	s_add_u32 s8, s8, s5
	s_addc_u32 s9, s9, 0
	s_mulk_i32 s9, 0x1340
	s_mul_hi_u32 s27, s8, 0x1340
	s_add_i32 s27, s27, s9
	s_mulk_i32 s8, 0x1340
	s_add_u32 s8, s6, s8
	v_lshrrev_b32_e32 v3, 2, v2
	s_addc_u32 s9, s7, s27
	v_and_or_b32 v16, v3, 3, v133
	v_lshlrev_b32_e32 v3, 1, v2
	v_lshlrev_b32_e32 v2, 3, v2
	v_lshl_add_u64 v[10:11], s[8:9], 0, v[134:135]
	v_and_b32_e32 v17, 32, v3
	v_and_b32_e32 v18, 24, v2
	global_load_dwordx4 v[2:5], v[6:7], off offset:3584
	s_nop 0
	global_load_dwordx4 v[6:9], v[6:7], off offset:3840
	s_bitcmp1_b32 s30, 0
	global_load_dwordx4 v[10:13], v[10:11], off offset:3584
	s_cselect_b64 s[8:9], -1, 0
	s_and_b64 s[70:71], s[8:9], exec
	s_cselect_b32 s40, 0x6400, 0
	s_add_i32 s27, s40, 0
	s_bitcmp1_b32 s26, 0
	s_cselect_b32 s70, 0x6400, 0
	v_add_u32_e32 v19, s27, v132
	s_add_i32 s70, s70, 0
	v_mad_u32_u24 v164, v34, s73, v0
	v_mul_u32_u24_e32 v0, 0x140, v16
	v_add3_u32 v131, 0, v15, v14
	v_or3_b32 v141, v0, v17, v18
	v_add_u32_e32 v0, s27, v164
	s_add_i32 s27, s41, s63
	s_lshl_b32 s41, s30, 6
	v_add_u32_e32 v165, 0, v141
	s_waitcnt vmcnt(2)
	ds_write_b128 v19, v[2:5]
	v_add_u32_e32 v2, s70, v132
	s_waitcnt vmcnt(1)
	ds_write_b128 v131, v[6:9] offset:51200
	s_waitcnt vmcnt(0)
	ds_write_b128 v2, v[10:13]
	s_waitcnt lgkmcnt(0)
	s_barrier
	ds_read_b128 v[2:5], v0 offset:4608
	ds_read_b128 v[6:9], v0
	ds_read_b128 v[36:39], v0 offset:32
	s_waitcnt lgkmcnt(1)
	v_mfma_f32_32x32x16_bf16 v[18:33], v[6:9], v[82:85], 0
	ds_read_b128 v[40:43], v0 offset:4640
	v_mfma_f32_32x32x16_bf16 v[2:17], v[2:5], v[82:85], 0
	s_waitcnt lgkmcnt(1)
	v_mfma_f32_32x32x16_bf16 v[18:33], v[36:39], v[86:89], v[18:33]
	s_waitcnt lgkmcnt(0)
	v_mfma_f32_32x32x16_bf16 v[2:17], v[40:43], v[86:89], v[2:17]
	ds_read_b128 v[36:39], v0 offset:64
	ds_read_b128 v[40:43], v0 offset:4672
	s_waitcnt lgkmcnt(1)
	v_mfma_f32_32x32x16_bf16 v[18:33], v[36:39], v[90:93], v[18:33]
	s_waitcnt lgkmcnt(0)
	v_mfma_f32_32x32x16_bf16 v[2:17], v[40:43], v[90:93], v[2:17]
	ds_read_b128 v[36:39], v0 offset:96
	ds_read_b128 v[40:43], v0 offset:4704
	v_or_b32_e32 v0, s15, v34
	s_add_i32 s15, s41, 0x100
	v_or_b32_e32 v34, s15, v133
	v_sub_u32_e32 v45, v34, v0
	v_add_u32_e32 v52, 16, v45
	v_med3_i32 v34, v45, 0, v216
	s_waitcnt lgkmcnt(1)
	v_mfma_f32_32x32x16_bf16 v[18:33], v[36:39], v[94:97], v[18:33]
	v_add_u32_e32 v38, 2, v45
	v_med3_i32 v39, v38, 0, v216
	v_med3_i32 v38, v38, s46, v217
	v_med3_i32 v53, v52, 0, v216
	v_med3_i32 v54, v52, s46, v217
	v_lshl_add_u32 v34, v34, 2, s27
	v_lshl_add_u32 v38, v38, 2, s27
	v_lshl_add_u32 v52, v53, 2, s27
	v_lshl_add_u32 v53, v54, 2, s27
	s_waitcnt lgkmcnt(0)
	s_barrier
; #define LAS __attribute__((address_space(3)))
; __device__ __forceinline__ float swapmax(float m) { auto rr = __builtin_amdgcn_permlane32_swap(__float_as_uint(m), __float_as_uint(m), false, false); return fmaxf(__uint_as_float(rr[0]), __uint_as_float(rr[1])); }
; #define A2_TILE_BIAS(t, cbv, nearv) do { cbv = 0.f; nearv = (MODE == 2); if (MODE == 0) { const int ks_ = 64 * (t); const int maxrel_ = ks_ + 63 - qslot0, minrel_ = ks_ - (qslot0 + 31); \
;         const bool lf_ = maxrel_ <= -91, rt_ = minrel_ >= 91; cbv = lf_ ? tabL : (rt_ ? tabR : 0.f); nearv = !(lf_ || rt_); } } while (0)
; #define A4_BIAS(t, SA, SB) do { \
;         const int relb = 64 * (t) + 4 * hi - (qslot0 + r32) + 256; \
;         _Pragma("unroll") for (int r = 0; r < 16; ++r) { const int c = (r & 3) + 8 * (r >> 2); \
;             int i0 = relb + c, i1 = relb + c + 32; i0 = i0 < 0 ? 0 : (i0 > 511 ? 511 : i0); i1 = i1 < 0 ? 0 : (i1 > 511 ? 511 : i1); \
;             SA[r] += mytab[i0]; SB[r] += mytab[i1]; } } while (0)
; template <int MODE> __device__ __forceinline__ void attn_unit4(LAS unsigned char* lds, const int uidx, const AttnArgs& A) {
;     ...
;     float cbc; bool nearc;
;     A2_TILE_BIAS(t0, cbc, nearc);
;     { const float zero_ = 0.f; A2_QK(s0, s1, t0 & 1, zero_); }
;     __syncthreads();
;     if (MODE != 1 && nearc) A4_BIAS(t0, s0, s1);
;     if (t0 == 1) {
; #pragma unroll
;         for (int r = 0; r < 16; ++r) { const int c = (r & 3) + 8 * (r >> 2) + 4 * hi; s0[r] = negbig; if (c < 16) s1[r] = negbig; }
;     }
;     float mref;
;     { float mx = fmaxf(s0[0], s1[0]);
; #pragma unroll
;       for (int r = 1; r < 16; ++r) mx = fmaxf(mx, fmaxf(s0[r], s1[r]));
;       mx = swapmax(mx) + cbc; mref = fmaxf(mx, -30.0f);
;     ...
;     { const LAS unsigned char* vb_ = lds + VBASE + vs_cur * VSTG + vfrag; const LAS unsigned char* kb_ = lds; bf16x8 fa[NM];
; #pragma unroll
;       for (int i = 0; i < PF; ++i) { A3_LOADF(i); fan[i] = fa[i]; } }
;     if (wid >= 4) __builtin_amdgcn_s_setprio(1);
	ds_read_b32 v36, v34
	ds_read_b32 v38, v38 offset:128
	ds_read_b32 v52, v52
	ds_read_b32 v54, v53 offset:128
	v_add_u32_e32 v53, 17, v45
	v_med3_i32 v35, v45, s46, v217
	v_med3_i32 v55, v53, 0, v216
	v_med3_i32 v56, v53, s46, v217
	v_lshl_add_u32 v34, v35, 2, s27
	v_add_u32_e32 v35, 1, v45
	v_lshl_add_u32 v53, v55, 2, s27
	v_lshl_add_u32 v55, v56, 2, s27
	v_add_u32_e32 v56, 18, v45
	v_med3_i32 v37, v35, 0, v216
	v_med3_i32 v57, v56, 0, v216
	v_med3_i32 v58, v56, s46, v217
	v_lshl_add_u32 v37, v37, 2, s27
	v_lshl_add_u32 v39, v39, 2, s27
	v_lshl_add_u32 v56, v57, 2, s27
	v_lshl_add_u32 v57, v58, 2, s27
	ds_read_b32 v37, v37
	ds_read_b32 v46, v39
	ds_read_b32 v53, v53
	ds_read_b32 v58, v57 offset:128
	v_add_u32_e32 v57, 19, v45
	v_med3_i32 v59, v57, 0, v216
	v_med3_i32 v60, v57, s46, v217
	v_lshl_add_u32 v57, v59, 2, s27
	v_lshl_add_u32 v59, v60, 2, s27
	v_add_u32_e32 v60, 24, v45
	v_med3_i32 v61, v60, 0, v216
	v_med3_i32 v62, v60, s46, v217
	v_lshl_add_u32 v60, v61, 2, s27
	v_lshl_add_u32 v61, v62, 2, s27
	v_add_u32_e32 v39, 3, v45
	ds_read_b32 v62, v61 offset:128
	v_add_u32_e32 v61, 25, v45
	v_mfma_f32_32x32x16_bf16 v[2:17], v[40:43], v[94:97], v[2:17]
	v_med3_i32 v40, v39, 0, v216
	v_med3_i32 v39, v39, s46, v217
	v_med3_i32 v63, v61, 0, v216
	v_lshl_add_u32 v40, v40, 2, s27
	v_lshl_add_u32 v39, v39, 2, s27
	v_med3_i32 v64, v61, s46, v217
	v_lshl_add_u32 v61, v63, 2, s27
	ds_read_b32 v47, v40
	ds_read_b32 v55, v55 offset:128
	ds_read_b32 v61, v61
	ds_read_b32 v39, v39 offset:128
	ds_read_b32 v34, v34 offset:128
	v_add_u32_e32 v40, 8, v45
	v_med3_i32 v41, v40, 0, v216
	v_med3_i32 v40, v40, s46, v217
	v_lshl_add_u32 v41, v41, 2, s27
	v_lshl_add_u32 v40, v40, 2, s27
	v_lshl_add_u32 v63, v64, 2, s27
	ds_read_b32 v48, v41
	ds_read_b32 v56, v56
	ds_read_b32 v63, v63 offset:128
	ds_read_b32 v40, v40 offset:128
	v_add_u32_e32 v41, 9, v45
	v_add_u32_e32 v64, 26, v45
	v_med3_i32 v42, v41, 0, v216
	v_med3_i32 v41, v41, s46, v217
	v_med3_i32 v65, v64, 0, v216
	v_med3_i32 v35, v35, s46, v217
	v_lshl_add_u32 v42, v42, 2, s27
	v_lshl_add_u32 v41, v41, 2, s27
	v_med3_i32 v66, v64, s46, v217
	v_lshl_add_u32 v64, v65, 2, s27
	v_lshl_add_u32 v35, v35, 2, s27
	ds_read_b32 v49, v42
	ds_read_b32 v57, v57
	ds_read_b32 v64, v64
	ds_read_b32 v41, v41 offset:128
	v_add_u32_e32 v42, 10, v45
	ds_read_b32 v35, v35 offset:128
	v_med3_i32 v43, v42, 0, v216
	v_med3_i32 v42, v42, s46, v217
	v_lshl_add_u32 v43, v43, 2, s27
	v_lshl_add_u32 v42, v42, 2, s27
	v_lshl_add_u32 v65, v66, 2, s27
	ds_read_b32 v50, v43
	ds_read_b32 v59, v59 offset:128
	ds_read_b32 v66, v65 offset:128
	ds_read_b32 v42, v42 offset:128
	v_add_u32_e32 v43, 11, v45
	v_add_u32_e32 v45, 27, v45
	v_med3_i32 v65, v45, 0, v216
	v_med3_i32 v45, v45, s46, v217
	s_waitcnt lgkmcnt(14)
	v_pk_add_f32 v[18:19], v[18:19], v[36:37]
	v_lshl_add_u32 v36, v45, 2, s27
	v_med3_i32 v51, v43, 0, v216
	v_med3_i32 v43, v43, s46, v217
	ds_read_b32 v67, v36 offset:128
	s_waitcnt lgkmcnt(5)
	v_pk_add_f32 v[2:3], v[2:3], v[34:35]
	v_lshl_add_u32 v51, v51, 2, s27
	v_lshl_add_u32 v43, v43, 2, s27
	v_lshl_add_u32 v65, v65, 2, s27
	v_pk_add_f32 v[20:21], v[20:21], v[46:47]
	v_pk_add_f32 v[4:5], v[4:5], v[38:39]
	v_cndmask_b32_e32 v3, v3, v44, vcc
	v_cndmask_b32_e32 v19, v19, v44, vcc
	ds_read_b32 v51, v51
	ds_read_b32 v60, v60
	ds_read_b32 v65, v65
	ds_read_b32 v43, v43 offset:128
	v_cndmask_b32_e32 v4, v4, v44, vcc
	v_cndmask_b32_e32 v20, v20, v44, vcc
	v_max_f32_e32 v34, v3, v3
	v_max_f32_e32 v35, v19, v19
	v_cndmask_b32_e32 v5, v5, v44, vcc
	v_cndmask_b32_e32 v21, v21, v44, vcc
	v_max_f32_e32 v34, v35, v34
	v_max_f32_e32 v35, v4, v4
	v_max_f32_e32 v36, v20, v20
	v_pk_add_f32 v[22:23], v[22:23], v[48:49]
	v_pk_add_f32 v[6:7], v[6:7], v[40:41]
	v_cndmask_b32_e32 v2, v2, v44, vcc
	v_cndmask_b32_e32 v18, v18, v44, vcc
	v_max_f32_e32 v35, v36, v35
	v_max_f32_e32 v36, v5, v5
	v_max_f32_e32 v37, v21, v21
	v_cndmask_b32_e32 v6, v6, v44, vcc
	v_cndmask_b32_e32 v22, v22, v44, vcc
	v_max3_f32 v34, v18, v2, v34
	v_max_f32_e32 v36, v37, v36
	v_cndmask_b32_e32 v7, v7, v44, vcc
	v_cndmask_b32_e32 v23, v23, v44, vcc
	v_max3_f32 v34, v34, v35, v36
	v_max_f32_e32 v35, v6, v6
	v_max_f32_e32 v36, v22, v22
	s_waitcnt lgkmcnt(3)
	v_pk_add_f32 v[24:25], v[24:25], v[50:51]
	s_waitcnt lgkmcnt(0)
	v_pk_add_f32 v[8:9], v[8:9], v[42:43]
	v_max_f32_e32 v35, v36, v35
	v_max_f32_e32 v36, v7, v7
	v_max_f32_e32 v37, v23, v23
	v_cndmask_b32_e32 v8, v8, v44, vcc
	v_cndmask_b32_e32 v24, v24, v44, vcc
	v_max_f32_e32 v36, v37, v36
	v_cndmask_b32_e32 v9, v9, v44, vcc
	v_cndmask_b32_e32 v25, v25, v44, vcc
	v_max3_f32 v34, v34, v35, v36
	v_max_f32_e32 v35, v8, v8
	v_max_f32_e32 v36, v24, v24
	v_pk_add_f32 v[26:27], v[26:27], v[52:53]
	v_max_f32_e32 v35, v36, v35
	v_max_f32_e32 v36, v9, v9
	v_max_f32_e32 v37, v25, v25
	v_cndmask_b32_e32 v27, v27, v44, vcc
	v_cndmask_b32_e32 v26, v26, v44, vcc
	v_max_f32_e32 v36, v37, v36
	v_pk_add_f32 v[28:29], v[28:29], v[56:57]
	v_pk_add_f32 v[10:11], v[10:11], v[54:55]
	v_max3_f32 v34, v34, v35, v36
	v_max_f32_e32 v35, v26, v26
	v_max_f32_e32 v36, v27, v27
	ds_read_b64_tr_b16 v[126:127], v165 offset:51200
	ds_read_b64_tr_b16 v[128:129], v165 offset:53760
	ds_read_b64_tr_b16 v[122:123], v165 offset:51264
	ds_read_b64_tr_b16 v[124:125], v165 offset:53824
	ds_read_b64_tr_b16 v[118:119], v165 offset:56320
	ds_read_b64_tr_b16 v[120:121], v165 offset:58880
	ds_read_b64_tr_b16 v[114:115], v165 offset:56384
	ds_read_b64_tr_b16 v[116:117], v165 offset:58944
	v_cndmask_b32_e32 v29, v29, v44, vcc
	v_cndmask_b32_e32 v28, v28, v44, vcc
	v_max_f32_e32 v35, v35, v10
	v_max_f32_e32 v36, v36, v11
	v_pk_add_f32 v[30:31], v[30:31], v[60:61]
	v_pk_add_f32 v[12:13], v[12:13], v[58:59]
	v_max3_f32 v34, v34, v35, v36
	v_max_f32_e32 v35, v28, v28
	v_max_f32_e32 v36, v29, v29
	v_cndmask_b32_e32 v31, v31, v44, vcc
	v_cndmask_b32_e32 v30, v30, v44, vcc
	v_max_f32_e32 v35, v35, v12
	v_max_f32_e32 v36, v36, v13
	v_pk_add_f32 v[32:33], v[32:33], v[64:65]
	v_pk_add_f32 v[14:15], v[14:15], v[62:63]
	v_max3_f32 v34, v34, v35, v36
	v_max_f32_e32 v35, v30, v30
	v_max_f32_e32 v36, v31, v31
	v_cndmask_b32_e32 v33, v33, v44, vcc
	v_cndmask_b32_e32 v32, v32, v44, vcc
	v_max_f32_e32 v35, v35, v14
	v_max_f32_e32 v36, v36, v15
	v_pk_add_f32 v[16:17], v[16:17], v[66:67]
	v_max3_f32 v34, v34, v35, v36
	v_max_f32_e32 v35, v32, v32
	v_max_f32_e32 v36, v33, v33
	v_max_f32_e32 v35, v35, v16
	v_max_f32_e32 v36, v36, v17
	v_max3_f32 v34, v34, v35, v36
	v_mov_b32_e32 v35, v34
	s_nop 1
	v_permlane32_swap_b32_e32 v34, v35
	s_cmp_lt_i32 s14, 4
	s_cbranch_scc0 .LBB0_932
	s_setprio 1

; template <int MODE> __device__ __forceinline__ void attn_unit4(LAS unsigned char* lds, const int uidx, const AttnArgs& A) {
;     ...
;     const GAS bf16_t *Kg, *Vg, *Qg; int kld, vld;
;     if (MODE == 0) { Kg = (const GAS bf16_t*)A.U + 512 + hx * 128; kld = DIN; Vg = (const GAS bf16_t*)A.U + 1024 + hx * 128; vld = DIN; Qg = (const GAS bf16_t*)A.U + hx * 128 + st * 64; }
;     else if (MODE == 1) { Kg = (const GAS bf16_t*)A.KC + hx * 192; kld = 384; Vg = (const GAS bf16_t*)A.VC + hx * 128; vld = 256; Qg = (const GAS bf16_t*)A.U + 2048 + (2 * hx + st) * 96; }
;     else { Kg = (const GAS bf16_t*)A.U + 1792 + hx * 64; kld = DIN; Vg = (const GAS bf16_t*)A.U + 1920 + hx * 64; vld = DIN; Qg = (const GAS bf16_t*)A.U + 1536 + (2 * hx + st) * 64; }
;     int t0 = 1, t1 = 130;
;     if (MODE == 2) { t0 = 2 * (qb - 1); if (t0 < 1) t0 = 1; t1 = 2 * (qb + 2); if (t1 > 130) t1 = 130; }
;     LAS float* tab = (LAS float*)(lds + TABOFF);
;     if (MODE != 1) {
;         const int rel = tid - 256; const int bk = t5_bucket_dev(rel);
;         if (MODE == 0) { tab[tid] = A.rel_bias[bk * 8 + hx] * LOG2E; }
;         else { const bool okw = (rel <= 128 && rel >= -128);
;             tab[tid] = okw ? A.rel_bias[bk * 8 + 4 + 2 * hx] * LOG2E : negbig; tab[512 + tid] = okw ? A.rel_bias[bk * 8 + 4 + 2 * hx + 1] * LOG2E : negbig; }
;     }
;     const int qslot0 = qb * 128 + qg * 32;
;     bf16x8 qf[NKC];
;     { const GAS bf16_t* qp = Qg + (row0 + qslot0 + r32) * DIN + hi * 8;
; #pragma unroll
;       for (int kc = 0; kc < NKC; ++kc) qf[kc] = *(const GAS bf16x8*)(qp + kc * 16); }
;     int ksrc[NKL], kdst[NKL], vsrc[NVL], vdst[NVL];
; #pragma unroll
;     for (int i = 0; i < NKL; ++i) { const int id = tid + NTHR * i, key = id / KCH, ch = id % KCH; ksrc[i] = key * kld + ch * 8; kdst[i] = key * KSTR + ch * 16; }
; #pragma unroll
;     for (int i = 0; i < NVL; ++i) { const int id = tid + NTHR * i, key = id / VCH, ch = id % VCH; vsrc[i] = key * vld + ch * 8; vdst[i] = VBASE + key * VSTR + ch * 16; }
;     ...
;     {
;       u32x4 kst2[NKL];
;       A2_ISSUE_K(t0); A2_ISSUE_V(t0);
;       { const GAS bf16_t* kp_ = Kg + (row0 + 64 * (size_t)(t0 + 1)) * kld;
; #pragma unroll
;         for (int i = 0; i < NKL; ++i) kst2[i] = *(const GAS u32x4*)(kp_ + ksrc[i]); }
;       A2_COMMIT_K(t0 & 1); A2_COMMIT_V(0);
;       { LAS unsigned char* bb_ = lds + ((t0 + 1) & 1) * KSTG;
; #pragma unroll
.LBB0_954:
	s_and_b64 vcc, exec, s[0:1]
	s_cbranch_vccz .LBB0_969
	v_mov_b32_e32 v6, v252
	s_add_i32 s5, s36, 0xf5d8
	v_readfirstlane_b32 s0, v6
	s_ashr_i32 s4, s0, 6
	s_ashr_i32 s14, s0, 8
	s_and_b32 s0, s5, 0xffff
	s_mul_i32 s6, s0, 0xfc1
	s_lshr_b32 s1, s6, 18
	s_mul_i32 s7, s1, 0x41
	s_bfe_u32 s8, s6, 0x10012
	s_sub_i32 s9, s5, s7
	s_lshr_b32 s5, s6, 19
	s_lshl_b32 s6, s8, 1
	s_add_i32 s6, s14, s6
	s_mul_i32 s26, s6, 0x60
	s_ashr_i32 s27, s26, 31
	s_lshl_b64 s[26:27], s[26:27], 1
	v_readlane_b32 s15, v254, 59
	s_add_u32 s26, s15, s26
	v_readlane_b32 s15, v255, 0
	s_addc_u32 s27, s15, s27
	s_lshl_b32 s9, s9, 7
	s_mul_i32 s7, s5, 0x2080
	s_and_b32 s9, s9, 0xff80
	s_lshl_b32 s15, s4, 5
	s_and_b32 s15, s15, 0x60
	s_add_i32 s9, s7, s9
	v_and_b32_e32 v7, 31, v6
	s_or_b32 s9, s15, s9
	v_bfe_u32 v8, v6, 5, 1
	v_or_b32_e32 v0, s9, v7
	v_mov_b64_e32 v[2:3], s[26:27]
	v_mad_u64_u32 v[2:3], s[26:27], v0, s45, v[2:3]
	v_lshlrev_b32_e32 v4, 4, v8
	v_mov_b32_e32 v5, v1
	v_mov_b32_e32 v18, 0xf149f2ca
	v_lshl_add_u64 v[2:3], v[2:3], 0, v[4:5]
	s_mov_b32 s9, 0x2aaaaaab
	global_load_dwordx4 v[114:117], v[2:3], off
	global_load_dwordx4 v[118:121], v[2:3], off offset:32
	global_load_dwordx4 v[122:125], v[2:3], off offset:64
	global_load_dwordx4 v[126:129], v[2:3], off offset:96
	global_load_dwordx4 v[130:133], v[2:3], off offset:128
	global_load_dwordx4 v[134:137], v[2:3], off offset:160
	v_mul_hi_i32 v2, v6, s9
	v_lshrrev_b32_e32 v3, 31, v2
	v_ashrrev_i32_e32 v2, 2, v2
	v_add_u32_e32 v2, v2, v3
	v_mul_lo_u32 v3, v2, 24
	s_movk_i32 s15, 0x180
	s_movk_i32 s26, 0x190
	v_sub_u32_e32 v3, v6, v3
	v_mul_lo_u32 v5, v2, s15
	v_mul_lo_u32 v2, v2, s26
	v_lshl_add_u32 v19, v3, 4, v2
	v_add_u32_e32 v2, 0x200, v6
	v_lshl_add_u32 v168, v3, 3, v5
	v_mul_hi_i32 v3, v2, s9
	v_lshrrev_b32_e32 v5, 31, v3
	v_ashrrev_i32_e32 v3, 2, v3
	v_add_u32_e32 v3, v3, v5
	v_mul_lo_u32 v5, v3, 24
	v_sub_u32_e32 v5, v2, v5
	v_mul_lo_u32 v9, v3, s15
	v_mul_lo_u32 v3, v3, s26
	v_lshl_add_u32 v36, v5, 4, v3
	v_add_u32_e32 v3, 0x400, v6
	v_lshl_add_u32 v174, v5, 3, v9
	v_mul_hi_i32 v5, v3, s9
	v_lshrrev_b32_e32 v9, 31, v5
	v_ashrrev_i32_e32 v5, 2, v5
	v_add_u32_e32 v5, v5, v9
	v_mul_lo_u32 v9, v5, 24
	v_sub_u32_e32 v3, v3, v9
	v_mul_lo_u32 v9, v5, s15
	v_mul_lo_u32 v5, v5, s26
	v_lshl_add_u32 v176, v3, 3, v9
	v_lshl_add_u32 v37, v3, 4, v5
	v_ashrrev_i32_e32 v3, 31, v6
	v_lshrrev_b32_e32 v3, 28, v3
	v_add_u32_e32 v3, v6, v3
	v_ashrrev_i32_e32 v5, 4, v3
	v_and_b32_e32 v3, -16, v3
	v_sub_u32_e32 v38, v6, v3
	v_lshlrev_b32_e32 v3, 3, v38
	v_lshl_add_u32 v170, v5, 8, v3
	v_ashrrev_i32_e32 v3, 31, v2
	v_lshrrev_b32_e32 v3, 28, v3
	s_movk_i32 s40, 0x140
	v_add_u32_e32 v3, v2, v3
	s_mul_i32 s9, s8, 0x180
	v_mul_lo_u32 v39, v5, s40
	v_ashrrev_i32_e32 v5, 4, v3
	v_and_b32_e32 v3, -16, v3
	s_add_u32 s26, s22, s9
	v_sub_u32_e32 v40, v2, v3
	s_addc_u32 s27, s23, 0
	v_lshlrev_b32_e32 v2, 3, v40
	s_or_b32 s15, s7, 64
	v_lshl_add_u32 v172, v5, 8, v2
	s_mul_i32 s9, s14, 0xc0
	v_mul_u32_u24_e32 v2, 0x190, v7
	s_mul_i32 s30, s15, 0x300
	v_add3_u32 v42, v4, v2, s9
	s_mul_hi_u32 s9, s15, 0x300
	s_add_u32 s38, s26, s30
	s_addc_u32 s39, s27, s9
	s_lshl_b32 s8, s8, 8
	s_add_u32 s8, s24, s8
	s_addc_u32 s9, s25, 0
	s_lshl_b32 s14, s14, 7
	v_mov_b32_e32 v15, s14
	s_lshl_b32 s14, s15, 9
	v_lshlrev_b32_e32 v196, 2, v8
	v_lshrrev_b32_e32 v2, 2, v6
	s_add_u32 s14, s8, s14
	v_and_or_b32 v14, v2, 3, v196
	s_addc_u32 s15, s9, 0
	v_ashrrev_i32_e32 v171, 31, v170
	v_ashrrev_i32_e32 v173, 31, v172
	s_mul_i32 s5, s5, 0x618000
	v_lshlrev_b32_e32 v2, 1, v6
	v_ashrrev_i32_e32 v169, 31, v168
	v_ashrrev_i32_e32 v175, 31, v174
	v_ashrrev_i32_e32 v177, 31, v176
	v_mad_u32_u24 v45, v14, s40, v15
	v_lshl_add_u64 v[14:15], v[170:171], 1, s[14:15]
	v_lshl_add_u64 v[20:21], v[172:173], 1, s[14:15]
	s_mul_hi_u32 s15, s7, 0x300
	s_add_u32 s14, s26, s5
	v_and_b32_e32 v43, 32, v2
	v_lshlrev_b32_e32 v2, 3, v6
	v_lshlrev_b64 v[24:25], 1, v[168:169]
	v_lshlrev_b64 v[28:29], 1, v[174:175]
	v_lshlrev_b64 v[32:33], 1, v[176:177]
	s_addc_u32 s15, s27, s15
	v_and_b32_e32 v44, 24, v2
	v_lshl_add_u64 v[2:3], s[38:39], 0, v[24:25]
	v_lshl_add_u64 v[6:7], s[38:39], 0, v[28:29]
	v_lshl_add_u64 v[10:11], s[38:39], 0, v[32:33]
	s_add_u32 s38, s14, 0x18000
	s_addc_u32 s39, s15, 0
	v_mul_lo_u32 v41, v5, s40
	global_load_dwordx4 v[2:5], v[2:3], off
	v_lshl_add_u64 v[24:25], s[38:39], 0, v[24:25]
	global_load_dwordx4 v[6:9], v[6:7], off
	v_lshl_add_u64 v[28:29], s[38:39], 0, v[28:29]
	global_load_dwordx4 v[10:13], v[10:11], off
	v_lshl_add_u64 v[32:33], s[38:39], 0, v[32:33]
	global_load_dwordx4 v[14:17], v[14:15], off
	v_lshl_add_u32 v204, v38, 4, v39
	global_load_dwordx4 v[20:23], v[20:21], off
	v_lshl_add_u32 v205, v40, 4, v41
	global_load_dwordx4 v[24:27], v[24:25], off
	v_add_u32_e32 v202, 0, v19
	global_load_dwordx4 v[28:31], v[28:29], off
	v_add_u32_e32 v200, 0, v36
	global_load_dwordx4 v[32:35], v[32:33], off
	v_add_u32_e32 v201, 0, v37
	v_add_u32_e32 v199, 0, v204
	v_add_u32_e32 v198, 0, v205
	v_add_u32_e32 v206, 0, v42
	v_or3_b32 v203, v45, v43, v44
	v_add_u32_e32 v197, 0, v203
	s_cmp_lt_i32 s4, 4
	s_waitcnt vmcnt(7)
	ds_write_b128 v202, v[2:5] offset:25600
	s_waitcnt vmcnt(6)
	ds_write_b128 v200, v[6:9] offset:25600
	s_waitcnt vmcnt(5)
	ds_write_b128 v201, v[10:13] offset:25600
	s_waitcnt vmcnt(4)
	ds_write_b128 v199, v[14:17] offset:51200
	s_waitcnt vmcnt(3)
	ds_write_b128 v198, v[20:23] offset:51200
	s_waitcnt vmcnt(2)
	ds_write_b128 v202, v[24:27]
	s_waitcnt vmcnt(1)
	ds_write_b128 v200, v[28:31]
	s_waitcnt vmcnt(0)
	ds_write_b128 v201, v[32:35]
	s_waitcnt lgkmcnt(0)
	s_barrier
; #define LAS __attribute__((address_space(3)))
; __device__ __forceinline__ float swapmax(float m) { auto rr = __builtin_amdgcn_permlane32_swap(__float_as_uint(m), __float_as_uint(m), false, false); return fmaxf(__uint_as_float(rr[0]), __uint_as_float(rr[1])); }
; #define A4_BIAS(t, SA, SB) do { \
;         const int relb = 64 * (t) + 4 * hi - (qslot0 + r32) + 256; \
;         _Pragma("unroll") for (int r = 0; r < 16; ++r) { const int c = (r & 3) + 8 * (r >> 2); \
;             int i0 = relb + c, i1 = relb + c + 32; i0 = i0 < 0 ? 0 : (i0 > 511 ? 511 : i0); i1 = i1 < 0 ? 0 : (i1 > 511 ? 511 : i1); \
;             SA[r] += mytab[i0]; SB[r] += mytab[i1]; } } while (0)
; template <int MODE> __device__ __forceinline__ void attn_unit4(LAS unsigned char* lds, const int uidx, const AttnArgs& A) {
;     ...
;     { const float zero_ = 0.f; A2_QK(s0, s1, t0 & 1, zero_); }
;     __syncthreads();
;     if (MODE != 1 && nearc) A4_BIAS(t0, s0, s1);
;     if (t0 == 1) {
; #pragma unroll
;         for (int r = 0; r < 16; ++r) { const int c = (r & 3) + 8 * (r >> 2) + 4 * hi; s0[r] = negbig; if (c < 16) s1[r] = negbig; }
;     }
;     float mref;
;     { float mx = fmaxf(s0[0], s1[0]);
; #pragma unroll
;       for (int r = 1; r < 16; ++r) mx = fmaxf(mx, fmaxf(s0[r], s1[r]));
;       mx = swapmax(mx) + cbc; mref = fmaxf(mx, -30.0f);
;     ...
;     { const LAS unsigned char* vb_ = lds + VBASE + vs_cur * VSTG + vfrag; const LAS unsigned char* kb_ = lds; bf16x8 fa[NM];
; #pragma unroll
;       for (int i = 0; i < PF; ++i) { A3_LOADF(i); fan[i] = fa[i]; } }
;     if (wid >= 4) __builtin_amdgcn_s_setprio(1);
	ds_read_b128 v[2:5], v206 offset:38400
	ds_read_b128 v[20:23], v206 offset:38432
	s_waitcnt lgkmcnt(1)
	v_mfma_f32_32x32x16_bf16 v[2:17], v[2:5], v[114:117], 0
	s_waitcnt lgkmcnt(0)
	v_mfma_f32_32x32x16_bf16 v[2:17], v[20:23], v[118:121], v[2:17]
	ds_read_b128 v[20:23], v206 offset:38464
	s_waitcnt lgkmcnt(0)
	v_mfma_f32_32x32x16_bf16 v[2:17], v[20:23], v[122:125], v[2:17]
	ds_read_b128 v[20:23], v206 offset:38496
	s_waitcnt lgkmcnt(0)
	v_mfma_f32_32x32x16_bf16 v[2:17], v[20:23], v[126:129], v[2:17]
	ds_read_b128 v[20:23], v206 offset:38528
	s_waitcnt lgkmcnt(0)
	v_mfma_f32_32x32x16_bf16 v[2:17], v[20:23], v[130:133], v[2:17]
	ds_read_b128 v[20:23], v206 offset:38560
	s_waitcnt lgkmcnt(0)
	s_barrier
	ds_read_b64_tr_b16 v[106:107], v197 offset:51200
	ds_read_b64_tr_b16 v[108:109], v197 offset:53760
	ds_read_b64_tr_b16 v[102:103], v197 offset:51264
	ds_read_b64_tr_b16 v[104:105], v197 offset:53824
	ds_read_b64_tr_b16 v[94:95], v197 offset:56320
	ds_read_b64_tr_b16 v[96:97], v197 offset:58880
	ds_read_b64_tr_b16 v[90:91], v197 offset:56384
	ds_read_b64_tr_b16 v[92:93], v197 offset:58944
	v_mfma_f32_32x32x16_bf16 v[2:17], v[20:23], v[134:137], v[2:17]
	s_nop 11
	v_max_f32_e32 v2, v11, v11
	v_max_f32_e32 v3, v18, v18
	v_max_f32_e32 v2, v3, v2
	v_max_f32_e32 v4, v12, v12
	v_max_f32_e32 v5, v13, v13
	v_max3_f32 v2, v18, v10, v2
	v_max_f32_e32 v4, v3, v4
	v_max_f32_e32 v5, v3, v5
	v_max3_f32 v2, v2, v4, v5
	v_max_f32_e32 v4, v14, v14
	v_max_f32_e32 v5, v15, v15
	v_max_f32_e32 v4, v3, v4
	v_max_f32_e32 v5, v3, v5
	v_max3_f32 v2, v2, v4, v5
	v_max_f32_e32 v4, v16, v16
	v_max_f32_e32 v5, v17, v17
	v_max_f32_e32 v4, v3, v4
	v_max_f32_e32 v3, v3, v5
	v_max3_f32 v2, v2, v4, v3
	v_mov_b32_e32 v3, v2
	s_nop 1
	v_permlane32_swap_b32_e32 v2, v3
	s_cbranch_scc0 .LBB0_957
	s_setprio 1

; #define LAS __attribute__((address_space(3)))
; __device__ __forceinline__ float swapmax(float m) { auto rr = __builtin_amdgcn_permlane32_swap(__float_as_uint(m), __float_as_uint(m), false, false); return fmaxf(__uint_as_float(rr[0]), __uint_as_float(rr[1])); }
; template <int MODE> __device__ __forceinline__ void attn_unit4(LAS unsigned char* lds, const int uidx, const AttnArgs& A) {
;     ...
;     { float mx = fmaxf(s0[0], s1[0]);
; #pragma unroll
;       for (int r = 1; r < 16; ++r) mx = fmaxf(mx, fmaxf(s0[r], s1[r]));
;       mx = swapmax(mx) + cbc; mref = fmaxf(mx, -30.0f);
;     ...
;     { const LAS unsigned char* vb_ = lds + VBASE + vs_cur * VSTG + vfrag; const LAS unsigned char* kb_ = lds; bf16x8 fa[NM];
; #pragma unroll
;       for (int i = 0; i < PF; ++i) { A3_LOADF(i); fan[i] = fa[i]; } }
;     if (wid >= 4) __builtin_amdgcn_s_setprio(1);
.LBB0_981:
	v_lshrrev_b32_e32 v0, 2, v19
	v_and_or_b32 v0, v0, 3, v181
	s_nop 8
	v_lshlrev_b32_e32 v2, 1, v19
	v_lshlrev_b32_e32 v3, 3, v19
	v_mul_u32_u24_e32 v0, 0x140, v0
	v_and_b32_e32 v2, 32, v2
	v_and_b32_e32 v3, 24, v3
	v_or3_b32 v193, v0, v2, v3
	v_add_u32_e32 v192, 0, v193
	ds_read_b64_tr_b16 v[158:159], v192 offset:51200
	ds_read_b64_tr_b16 v[154:155], v192 offset:51264
	ds_read_b64_tr_b16 v[150:151], v192 offset:51328
	ds_read_b64_tr_b16 v[146:147], v192 offset:51392
	ds_read_b64_tr_b16 v[160:161], v192 offset:53760
	ds_read_b64_tr_b16 v[156:157], v192 offset:53824
	ds_read_b64_tr_b16 v[152:153], v192 offset:53888
	ds_read_b64_tr_b16 v[148:149], v192 offset:53952
	v_max_f32_e32 v0, v18, v18
	v_max_f32_e32 v2, v11, v11
	v_max_f32_e32 v2, v0, v2
	v_max_f32_e32 v3, v12, v12
	v_max_f32_e32 v4, v13, v13
	v_max3_f32 v2, v18, v10, v2
	v_max_f32_e32 v3, v0, v3
	v_max_f32_e32 v4, v0, v4
	v_max3_f32 v2, v2, v3, v4
	v_max_f32_e32 v3, v14, v14
	v_max_f32_e32 v4, v15, v15
	s_or_b32 s6, s71, 31
	v_max_f32_e32 v3, v0, v3
	v_max_f32_e32 v4, v0, v4
	s_cmpk_lt_i32 s6, 0xffe6
	v_max3_f32 v2, v2, v3, v4
	v_max_f32_e32 v3, v16, v16
	v_max_f32_e32 v4, v17, v17
	s_cselect_b64 vcc, -1, 0
	s_cmpk_gt_i32 s71, 0xd9
	v_max_f32_e32 v3, v0, v3
	v_max_f32_e32 v0, v0, v4
	s_cselect_b64 s[0:1], -1, 0
	v_max3_f32 v0, v2, v3, v0
	s_cmpk_gt_i32 s71, 0x119
	v_mov_b32_e32 v2, v0
	s_cselect_b64 s[4:5], -1, 0
	s_cmp_lt_i32 s6, 38
	s_cselect_b64 s[6:7], -1, 0
	s_cmp_lt_i32 s70, 4
	v_permlane32_swap_b32_e32 v0, v2
	s_cbranch_scc0 .LBB0_983
	s_setprio 1
